# P9/P13: sample rows spread over the even waves of every CU instead of all waves of half the CUs
# baseline (speedup 1.0000x reference)
.LBB0_1557:
	s_waitcnt vmcnt(15)
	v_pk_mul_f32 v[128:129], v[52:53], v[52:53]
	v_pk_mul_f32 v[132:133], v[50:51], v[50:51]
	s_and_b64 s[20:21], s[20:21], exec
	v_pk_mov_b32 v[134:135], v[132:133], v[128:129] op_sel:[1,0]
	v_mov_b32_e32 v133, v129
	v_pk_add_f32 v[128:129], v[134:135], v[132:133]
	s_waitcnt vmcnt(14)
	v_pk_mul_f32 v[132:133], v[60:61], v[60:61]
	v_pk_add_f32 v[128:129], v[128:129], v[128:129] op_sel_hi:[0,1]
	v_pk_mul_f32 v[134:135], v[58:59], v[58:59]
	s_waitcnt vmcnt(13)
	v_mul_f32_e32 v128, v54, v54
	v_pk_mov_b32 v[136:137], v[134:135], v[132:133] op_sel:[1,0]
	v_mov_b32_e32 v135, v133
	v_pk_add_f32 v[132:133], v[136:137], v[134:135]
	v_pk_fma_f32 v[134:135], v[54:55], v[54:55], v[128:129] op_sel_hi:[1,1,0]
	v_mul_f32_e32 v128, v56, v56
	v_pk_add_f32 v[132:133], v[132:133], v[132:133] op_sel_hi:[0,1]
	v_pk_fma_f32 v[136:137], v[56:57], v[56:57], v[128:129] op_sel_hi:[1,1,0]
	s_waitcnt vmcnt(12)
	v_mul_f32_e32 v134, v46, v46
	v_mul_f32_e32 v136, v47, v47
	v_mul_f32_e32 v132, v48, v48
	v_mul_f32_e32 v128, v49, v49
	v_pk_add_f32 v[134:135], v[134:135], v[136:137]
	v_pk_add_f32 v[128:129], v[132:133], v[128:129]
	s_waitcnt vmcnt(11)
	v_pk_mul_f32 v[132:133], v[32:33], v[32:33]
	v_pk_add_f32 v[128:129], v[134:135], v[128:129]
	v_pk_mul_f32 v[134:135], v[30:31], v[30:31]
	v_pk_add_f32 v[128:129], v[128:129], v[128:129] op_sel_hi:[0,1]
	v_pk_mov_b32 v[136:137], v[134:135], v[132:133] op_sel:[1,0]
	v_mov_b32_e32 v135, v133
	s_waitcnt vmcnt(10)
	v_mul_f32_e32 v128, v38, v38
	v_pk_add_f32 v[132:133], v[136:137], v[134:135]
	v_pk_fma_f32 v[134:135], v[38:39], v[38:39], v[128:129] op_sel_hi:[1,1,0]
	v_mul_f32_e32 v128, v40, v40
	v_pk_add_f32 v[132:133], v[132:133], v[132:133] op_sel_hi:[0,1]
	v_pk_fma_f32 v[136:137], v[40:41], v[40:41], v[128:129] op_sel_hi:[1,1,0]
	s_waitcnt vmcnt(9)
	v_mul_f32_e32 v134, v42, v42
	v_mul_f32_e32 v136, v43, v43
	v_mul_f32_e32 v132, v44, v44
	v_mul_f32_e32 v128, v45, v45
	v_pk_add_f32 v[134:135], v[134:135], v[136:137]
	v_pk_add_f32 v[128:129], v[132:133], v[128:129]
	s_waitcnt vmcnt(8)
	v_pk_mul_f32 v[132:133], v[36:37], v[36:37]
	v_pk_add_f32 v[128:129], v[134:135], v[128:129]
	v_pk_mul_f32 v[134:135], v[34:35], v[34:35]
	v_pk_add_f32 v[128:129], v[128:129], v[128:129] op_sel_hi:[0,1]
	v_pk_mov_b32 v[136:137], v[134:135], v[132:133] op_sel:[1,0]
	v_mov_b32_e32 v135, v133
	s_waitcnt vmcnt(7)
	v_mul_f32_e32 v128, v26, v26
	s_cselect_b32 s21, 0, s15
	s_cselect_b32 s20, s24, s14
	v_pk_add_f32 v[132:133], v[136:137], v[134:135]
	v_pk_fma_f32 v[134:135], v[26:27], v[26:27], v[128:129] op_sel_hi:[1,1,0]
	v_mul_f32_e32 v128, v28, v28
	s_cselect_b32 s24, s7, s5
	s_cselect_b32 s25, s6, s4
	s_lshl_b64 s[20:21], s[20:21], 14
	v_pk_add_f32 v[132:133], v[132:133], v[132:133] op_sel_hi:[0,1]
	v_pk_fma_f32 v[136:137], v[28:29], v[28:29], v[128:129] op_sel_hi:[1,1,0]
	s_add_u32 s20, s25, s20
	s_waitcnt vmcnt(6)
	v_mul_f32_e32 v134, v22, v22
	v_mul_f32_e32 v136, v23, v23
	v_mul_f32_e32 v132, v24, v24
	v_mul_f32_e32 v128, v25, v25
	s_addc_u32 s21, s24, s21
	v_pk_add_f32 v[134:135], v[134:135], v[136:137]
	v_pk_add_f32 v[128:129], v[132:133], v[128:129]
	s_waitcnt vmcnt(5)
	v_pk_mul_f32 v[132:133], v[20:21], v[20:21]
	v_pk_add_f32 v[128:129], v[134:135], v[128:129]
	global_load_dwordx4 v[134:137], v66, s[20:21]
	global_load_dwordx4 v[138:141], v[70:71], off
	v_pk_add_f32 v[128:129], v[128:129], v[128:129] op_sel_hi:[0,1]
	v_pk_mul_f32 v[142:143], v[18:19], v[18:19]
	s_waitcnt vmcnt(6)
	v_mul_f32_e32 v128, v14, v14
	v_pk_mov_b32 v[144:145], v[142:143], v[132:133] op_sel:[1,0]
	v_mov_b32_e32 v143, v133
	v_pk_add_f32 v[132:133], v[144:145], v[142:143]
	v_pk_fma_f32 v[142:143], v[14:15], v[14:15], v[128:129] op_sel_hi:[1,1,0]
	v_mul_f32_e32 v128, v16, v16
	v_pk_add_f32 v[132:133], v[132:133], v[132:133] op_sel_hi:[0,1]
	v_pk_fma_f32 v[144:145], v[16:17], v[16:17], v[128:129] op_sel_hi:[1,1,0]
	s_waitcnt vmcnt(5)
	v_mul_f32_e32 v142, v10, v10
	v_mul_f32_e32 v144, v11, v11
	v_mul_f32_e32 v132, v12, v12
	v_mul_f32_e32 v128, v13, v13
	v_pk_add_f32 v[142:143], v[142:143], v[144:145]
	v_pk_add_f32 v[128:129], v[132:133], v[128:129]
	s_waitcnt vmcnt(4)
	v_pk_mul_f32 v[132:133], v[4:5], v[4:5]
	v_pk_add_f32 v[128:129], v[142:143], v[128:129]
	v_pk_mul_f32 v[142:143], v[2:3], v[2:3]
	v_pk_add_f32 v[128:129], v[128:129], v[128:129] op_sel_hi:[0,1]
	v_pk_mov_b32 v[144:145], v[142:143], v[132:133] op_sel:[1,0]
	v_mov_b32_e32 v143, v133
	s_waitcnt vmcnt(3)
	v_mul_f32_e32 v128, v6, v6
	v_pk_add_f32 v[132:133], v[144:145], v[142:143]
	v_pk_fma_f32 v[142:143], v[6:7], v[6:7], v[128:129] op_sel_hi:[1,1,0]
	v_mul_f32_e32 v128, v8, v8
	v_pk_add_f32 v[132:133], v[132:133], v[132:133] op_sel_hi:[0,1]
	v_pk_fma_f32 v[144:145], v[8:9], v[8:9], v[128:129] op_sel_hi:[1,1,0]
	s_waitcnt vmcnt(2)
	v_mul_f32_e32 v142, v62, v62
	v_mul_f32_e32 v144, v63, v63
	v_mul_f32_e32 v132, v64, v64
	v_mul_f32_e32 v128, v65, v65
	v_pk_add_f32 v[142:143], v[142:143], v[144:145]
	v_pk_add_f32 v[128:129], v[132:133], v[128:129]
	v_lshl_add_u64 v[132:133], s[28:29], 0, v[124:125]
	v_pk_add_f32 v[128:129], v[142:143], v[128:129]
	v_lshl_add_u64 v[142:143], s[20:21], 0, v[66:67]
	v_add_f32_e32 v128, v128, v129
	ds_bpermute_b32 v129, v156, v128
	v_add_co_u32_e32 v144, vcc, s27, v142
	s_add_u32 s14, s14, s40
	s_nop 0
	v_addc_co_u32_e32 v145, vcc, 0, v143, vcc
	s_waitcnt lgkmcnt(0)
	v_add_f32_e32 v128, v128, v129
	ds_bpermute_b32 v129, v157, v128
	v_add_co_u32_e32 v146, vcc, s27, v132
	s_addc_u32 s15, s15, s41
	s_nop 0
	v_addc_co_u32_e32 v147, vcc, 0, v133, vcc
	s_waitcnt lgkmcnt(0)
	v_add_f32_e32 v128, v128, v129
	ds_bpermute_b32 v129, v158, v128
	v_add_co_u32_e32 v148, vcc, s52, v142
	v_lshl_add_u64 v[122:123], v[122:123], 0, s[8:9]
	s_nop 0
	v_addc_co_u32_e32 v149, vcc, 0, v143, vcc
	s_waitcnt lgkmcnt(0)
	v_add_f32_e32 v128, v128, v129
	ds_bpermute_b32 v129, v159, v128
	v_add_co_u32_e32 v150, vcc, s52, v132
	s_cmpk_lt_i32 s14, 0x2400
	s_nop 0
	v_addc_co_u32_e32 v151, vcc, 0, v133, vcc
	s_waitcnt lgkmcnt(0)
	v_add_f32_e32 v128, v128, v129
	ds_bpermute_b32 v129, v160, v128
	v_add_co_u32_e32 v142, vcc, s53, v142
	v_lshl_add_u64 v[124:125], v[124:125], 0, s[10:11]
	s_nop 0
	v_addc_co_u32_e32 v143, vcc, 0, v143, vcc
	s_waitcnt lgkmcnt(0)
	v_add_f32_e32 v128, v128, v129
	ds_bpermute_b32 v129, v161, v128
	s_waitcnt lgkmcnt(0)
	v_add_f32_e32 v128, v128, v129
	v_fmamk_f32 v128, v128, 0x39800000, v131
	v_rsq_f32_e32 v128, v128
	s_nop 0
	v_pk_mul_f32 v[50:51], v[50:51], v[128:129] op_sel_hi:[1,0]
	v_pk_mul_f32 v[52:53], v[52:53], v[128:129] op_sel_hi:[1,0]
	s_waitcnt vmcnt(0)
	v_pk_fma_f32 v[50:51], v[138:139], v[50:51], v[134:135]
	v_pk_fma_f32 v[52:53], v[140:141], v[52:53], v[136:137]
	global_store_dwordx4 v[132:133], v[50:53], off
	global_load_dwordx4 v[134:137], v66, s[20:21] offset:1024
	global_load_dwordx4 v[138:141], v[70:71], off offset:1024
	v_pk_mul_f32 v[60:61], v[60:61], v[128:129] op_sel_hi:[1,0]
	v_pk_mul_f32 v[58:59], v[58:59], v[128:129] op_sel_hi:[1,0]
	v_pk_mul_f32 v[56:57], v[56:57], v[128:129] op_sel_hi:[1,0]
	v_pk_mul_f32 v[54:55], v[54:55], v[128:129] op_sel_hi:[1,0]
	v_pk_mul_f32 v[46:47], v[46:47], v[128:129] op_sel_hi:[1,0]
	v_pk_mul_f32 v[48:49], v[48:49], v[128:129] op_sel_hi:[1,0]
	v_pk_mul_f32 v[32:33], v[32:33], v[128:129] op_sel_hi:[1,0]
	v_pk_mul_f32 v[30:31], v[30:31], v[128:129] op_sel_hi:[1,0]
	v_pk_mul_f32 v[40:41], v[40:41], v[128:129] op_sel_hi:[1,0]
	v_pk_mul_f32 v[38:39], v[38:39], v[128:129] op_sel_hi:[1,0]
	v_pk_mul_f32 v[42:43], v[42:43], v[128:129] op_sel_hi:[1,0]
	v_pk_mul_f32 v[44:45], v[44:45], v[128:129] op_sel_hi:[1,0]
	v_pk_mul_f32 v[36:37], v[36:37], v[128:129] op_sel_hi:[1,0]
	v_pk_mul_f32 v[34:35], v[34:35], v[128:129] op_sel_hi:[1,0]
	v_pk_mul_f32 v[28:29], v[28:29], v[128:129] op_sel_hi:[1,0]
	v_pk_mul_f32 v[26:27], v[26:27], v[128:129] op_sel_hi:[1,0]
	v_pk_mul_f32 v[22:23], v[22:23], v[128:129] op_sel_hi:[1,0]
	v_pk_mul_f32 v[24:25], v[24:25], v[128:129] op_sel_hi:[1,0]
	v_pk_mul_f32 v[20:21], v[20:21], v[128:129] op_sel_hi:[1,0]
	v_pk_mul_f32 v[18:19], v[18:19], v[128:129] op_sel_hi:[1,0]
	v_pk_mul_f32 v[16:17], v[16:17], v[128:129] op_sel_hi:[1,0]
	v_pk_mul_f32 v[14:15], v[14:15], v[128:129] op_sel_hi:[1,0]
	v_pk_mul_f32 v[10:11], v[10:11], v[128:129] op_sel_hi:[1,0]
	v_pk_mul_f32 v[12:13], v[12:13], v[128:129] op_sel_hi:[1,0]
	v_pk_mul_f32 v[4:5], v[4:5], v[128:129] op_sel_hi:[1,0]
	v_pk_mul_f32 v[2:3], v[2:3], v[128:129] op_sel_hi:[1,0]
	v_pk_mul_f32 v[8:9], v[8:9], v[128:129] op_sel_hi:[1,0]
	v_pk_mul_f32 v[6:7], v[6:7], v[128:129] op_sel_hi:[1,0]
	v_pk_mul_f32 v[62:63], v[62:63], v[128:129] op_sel_hi:[1,0]
	v_pk_mul_f32 v[64:65], v[64:65], v[128:129] op_sel_hi:[1,0]
	v_pk_mul_f32 v[128:129], v[52:53], v[52:53]
	s_waitcnt vmcnt(0)
	v_pk_fma_f32 v[58:59], v[138:139], v[58:59], v[134:135]
	v_pk_fma_f32 v[60:61], v[140:141], v[60:61], v[136:137]
	global_store_dwordx4 v[132:133], v[58:61], off offset:1024
	global_load_dwordx4 v[134:137], v66, s[20:21] offset:2048
	global_load_dwordx4 v[138:141], v[70:71], off offset:2048
	s_waitcnt vmcnt(0)
	v_pk_fma_f32 v[54:55], v[138:139], v[54:55], v[134:135]
	v_pk_fma_f32 v[56:57], v[140:141], v[56:57], v[136:137]
	global_store_dwordx4 v[132:133], v[54:57], off offset:2048
	global_load_dwordx4 v[134:137], v66, s[20:21] offset:3072
	global_load_dwordx4 v[138:141], v[70:71], off offset:3072
	s_waitcnt vmcnt(0)
	v_pk_fma_f32 v[48:49], v[140:141], v[48:49], v[136:137]
	v_pk_fma_f32 v[46:47], v[138:139], v[46:47], v[134:135]
	global_store_dwordx4 v[132:133], v[46:49], off offset:3072
	global_load_dwordx4 v[134:137], v[144:145], off offset:-4096
	global_load_dwordx4 v[138:141], v[72:73], off
	s_waitcnt vmcnt(0)
	v_pk_fma_f32 v[30:31], v[138:139], v[30:31], v[134:135]
	v_pk_fma_f32 v[32:33], v[140:141], v[32:33], v[136:137]
	global_store_dwordx4 v[146:147], v[30:33], off offset:-4096
	global_load_dwordx4 v[134:137], v[148:149], off offset:1024
	global_load_dwordx4 v[138:141], v[74:75], off
	s_waitcnt vmcnt(0)
	v_pk_fma_f32 v[38:39], v[138:139], v[38:39], v[134:135]
	v_pk_fma_f32 v[40:41], v[140:141], v[40:41], v[136:137]
	global_store_dwordx4 v[150:151], v[38:41], off offset:1024
	global_load_dwordx4 v[134:137], v[148:149], off offset:2048
	global_load_dwordx4 v[138:141], v[76:77], off
	s_waitcnt vmcnt(0)
	v_pk_fma_f32 v[44:45], v[140:141], v[44:45], v[136:137]
	v_pk_fma_f32 v[42:43], v[138:139], v[42:43], v[134:135]
	global_store_dwordx4 v[150:151], v[42:45], off offset:2048
	global_load_dwordx4 v[134:137], v[148:149], off offset:3072
	global_load_dwordx4 v[138:141], v[78:79], off
	s_waitcnt vmcnt(0)
	v_pk_fma_f32 v[34:35], v[138:139], v[34:35], v[134:135]
	v_pk_fma_f32 v[36:37], v[140:141], v[36:37], v[136:137]
	global_store_dwordx4 v[150:151], v[34:37], off offset:3072
	global_load_dwordx4 v[134:137], v[144:145], off
	global_load_dwordx4 v[138:141], v[80:81], off
	s_waitcnt vmcnt(0)
	v_pk_fma_f32 v[26:27], v[26:27], v[138:139], v[134:135]
	v_pk_fma_f32 v[28:29], v[28:29], v[140:141], v[136:137]
	global_store_dwordx4 v[146:147], v[26:29], off
	global_load_dwordx4 v[134:137], v[144:145], off offset:1024
	global_load_dwordx4 v[138:141], v[82:83], off
	s_waitcnt vmcnt(0)
	v_pk_fma_f32 v[24:25], v[24:25], v[140:141], v[136:137]
	v_pk_fma_f32 v[22:23], v[22:23], v[138:139], v[134:135]
	global_store_dwordx4 v[146:147], v[22:25], off offset:1024
	global_load_dwordx4 v[134:137], v[144:145], off offset:2048
	global_load_dwordx4 v[138:141], v[84:85], off
	s_waitcnt vmcnt(0)
	v_pk_fma_f32 v[18:19], v[18:19], v[138:139], v[134:135]
	v_pk_fma_f32 v[20:21], v[20:21], v[140:141], v[136:137]
	global_store_dwordx4 v[146:147], v[18:21], off offset:2048
	global_load_dwordx4 v[134:137], v[144:145], off offset:3072
	global_load_dwordx4 v[138:141], v[86:87], off
	v_add_co_u32_e32 v144, vcc, s53, v132
	s_waitcnt vmcnt(0)
	v_pk_fma_f32 v[14:15], v[14:15], v[138:139], v[134:135]
	v_pk_fma_f32 v[16:17], v[16:17], v[140:141], v[136:137]
	global_store_dwordx4 v[146:147], v[14:17], off offset:3072
	global_load_dwordx4 v[134:137], v[142:143], off
	global_load_dwordx4 v[138:141], v[88:89], off
	v_addc_co_u32_e32 v145, vcc, 0, v133, vcc
	s_waitcnt vmcnt(0)
	v_pk_fma_f32 v[12:13], v[12:13], v[140:141], v[136:137]
	v_pk_fma_f32 v[10:11], v[10:11], v[138:139], v[134:135]
	global_store_dwordx4 v[144:145], v[10:13], off
	global_load_dwordx4 v[132:135], v[142:143], off offset:1024
	global_load_dwordx4 v[136:139], v[90:91], off
	v_pk_mul_f32 v[140:141], v[50:51], v[50:51]
	s_waitcnt vmcnt(0)
	v_pk_fma_f32 v[2:3], v[2:3], v[136:137], v[132:133]
	v_pk_fma_f32 v[4:5], v[4:5], v[138:139], v[134:135]
	global_store_dwordx4 v[144:145], v[2:5], off offset:1024
	global_load_dwordx4 v[132:135], v[142:143], off offset:2048
	global_load_dwordx4 v[136:139], v[92:93], off
	s_waitcnt vmcnt(0)
	v_pk_fma_f32 v[6:7], v[6:7], v[136:137], v[132:133]
	v_pk_fma_f32 v[8:9], v[8:9], v[138:139], v[134:135]
	global_store_dwordx4 v[144:145], v[6:9], off offset:2048
	global_load_dwordx4 v[132:135], v[142:143], off offset:3072
	global_load_dwordx4 v[136:139], v[94:95], off
	v_pk_mov_b32 v[142:143], v[140:141], v[128:129] op_sel:[1,0]
	v_mov_b32_e32 v141, v129
	v_pk_add_f32 v[128:129], v[142:143], v[140:141]
	v_pk_mul_f32 v[140:141], v[58:59], v[58:59]
	v_pk_mul_f32 v[142:143], v[60:61], v[60:61]
	v_pk_add_f32 v[128:129], v[128:129], v[128:129] op_sel_hi:[0,1]
	v_pk_mov_b32 v[146:147], v[140:141], v[142:143] op_sel:[1,0]
	v_mov_b32_e32 v141, v143
	v_pk_add_f32 v[140:141], v[146:147], v[140:141]
	v_mul_f32_e32 v128, v54, v54
	v_pk_add_f32 v[140:141], v[140:141], v[140:141] op_sel_hi:[0,1]
	v_mul_f32_e32 v140, v56, v56
	v_pk_fma_f32 v[142:143], v[54:55], v[54:55], v[128:129] op_sel_hi:[1,1,0]
	v_pk_fma_f32 v[146:147], v[56:57], v[56:57], v[140:141] op_sel_hi:[1,1,0]
	v_mul_f32_e32 v142, v46, v46
	v_mul_f32_e32 v146, v47, v47
	v_mul_f32_e32 v128, v48, v48
	v_mul_f32_e32 v140, v49, v49
	v_pk_add_f32 v[142:143], v[142:143], v[146:147]
	v_pk_add_f32 v[128:129], v[128:129], v[140:141]
	v_pk_mul_f32 v[140:141], v[30:31], v[30:31]
	v_pk_add_f32 v[128:129], v[142:143], v[128:129]
	v_pk_mul_f32 v[142:143], v[32:33], v[32:33]
	v_pk_add_f32 v[128:129], v[128:129], v[128:129] op_sel_hi:[0,1]
	v_pk_mov_b32 v[146:147], v[140:141], v[142:143] op_sel:[1,0]
	v_mov_b32_e32 v141, v143
	v_pk_add_f32 v[140:141], v[146:147], v[140:141]
	v_mul_f32_e32 v128, v38, v38
	v_pk_add_f32 v[140:141], v[140:141], v[140:141] op_sel_hi:[0,1]
	v_mul_f32_e32 v140, v40, v40
	v_pk_fma_f32 v[142:143], v[38:39], v[38:39], v[128:129] op_sel_hi:[1,1,0]
	v_pk_fma_f32 v[146:147], v[40:41], v[40:41], v[140:141] op_sel_hi:[1,1,0]
	v_mul_f32_e32 v142, v42, v42
	v_mul_f32_e32 v146, v43, v43
	v_mul_f32_e32 v140, v44, v44
	v_mul_f32_e32 v128, v45, v45
	v_pk_add_f32 v[142:143], v[142:143], v[146:147]
	v_pk_add_f32 v[128:129], v[140:141], v[128:129]
	v_pk_mul_f32 v[140:141], v[34:35], v[34:35]
	v_pk_add_f32 v[128:129], v[142:143], v[128:129]
	v_pk_mul_f32 v[142:143], v[36:37], v[36:37]
	v_pk_add_f32 v[128:129], v[128:129], v[128:129] op_sel_hi:[0,1]
	v_pk_mov_b32 v[146:147], v[140:141], v[142:143] op_sel:[1,0]
	v_mov_b32_e32 v141, v143
	v_pk_add_f32 v[140:141], v[146:147], v[140:141]
	v_mul_f32_e32 v128, v26, v26
	v_pk_add_f32 v[140:141], v[140:141], v[140:141] op_sel_hi:[0,1]
	v_mul_f32_e32 v140, v28, v28
	v_pk_fma_f32 v[142:143], v[26:27], v[26:27], v[128:129] op_sel_hi:[1,1,0]
	v_pk_fma_f32 v[146:147], v[28:29], v[28:29], v[140:141] op_sel_hi:[1,1,0]
	v_mul_f32_e32 v142, v22, v22
	v_mul_f32_e32 v146, v23, v23
	v_mul_f32_e32 v140, v24, v24
	v_mul_f32_e32 v128, v25, v25
	v_pk_add_f32 v[142:143], v[142:143], v[146:147]
	v_pk_add_f32 v[128:129], v[140:141], v[128:129]
	v_pk_mul_f32 v[140:141], v[18:19], v[18:19]
	v_pk_add_f32 v[128:129], v[142:143], v[128:129]
	v_pk_mul_f32 v[142:143], v[20:21], v[20:21]
	v_pk_add_f32 v[128:129], v[128:129], v[128:129] op_sel:[0,1] op_sel_hi:[1,0]
	v_pk_mov_b32 v[146:147], v[140:141], v[142:143] op_sel:[1,0]
	v_mov_b32_e32 v141, v143
	v_pk_add_f32 v[140:141], v[146:147], v[140:141]
	v_mul_f32_e32 v142, v15, v15
	v_mul_f32_e32 v146, v17, v17
	v_pk_add_f32 v[140:141], v[140:141], v[140:141] op_sel:[0,1] op_sel_hi:[1,0]
	v_pk_fma_f32 v[142:143], v[14:15], v[14:15], v[142:143] op_sel_hi:[1,1,0]
	v_mul_f32_e32 v129, v10, v10
	v_mul_f32_e32 v141, v11, v11
	v_mul_f32_e32 v143, v12, v12
	v_pk_add_f32 v[128:129], v[128:129], v[140:141]
	s_waitcnt vmcnt(0)
	v_pk_fma_f32 v[64:65], v[64:65], v[138:139], v[134:135]
	v_pk_fma_f32 v[62:63], v[62:63], v[136:137], v[132:133]
	global_store_dwordx4 v[144:145], v[62:65], off offset:3072
	global_load_dwordx4 v[132:135], v[96:97], off
	v_pk_fma_f32 v[136:137], v[16:17], v[16:17], v[146:147] op_sel_hi:[1,1,0]
	v_mul_f32_e32 v139, v13, v13
	v_mov_b32_e32 v137, v139
	v_pk_add_f32 v[136:137], v[142:143], v[136:137]
	v_pk_mul_f32 v[138:139], v[4:5], v[4:5]
	v_pk_add_f32 v[128:129], v[128:129], v[136:137]
	v_pk_mul_f32 v[136:137], v[2:3], v[2:3]
	v_pk_add_f32 v[128:129], v[128:129], v[128:129] op_sel:[0,1] op_sel_hi:[1,0]
	v_pk_mov_b32 v[140:141], v[136:137], v[138:139] op_sel:[1,0]
	v_mov_b32_e32 v137, v139
	v_pk_add_f32 v[136:137], v[140:141], v[136:137]
	v_mul_f32_e32 v138, v7, v7
	v_mul_f32_e32 v140, v9, v9
	v_pk_add_f32 v[136:137], v[136:137], v[136:137] op_sel:[0,1] op_sel_hi:[1,0]
	v_pk_fma_f32 v[138:139], v[6:7], v[6:7], v[138:139] op_sel_hi:[1,1,0]
	v_pk_fma_f32 v[140:141], v[8:9], v[8:9], v[140:141] op_sel_hi:[1,1,0]
	v_mul_f32_e32 v129, v62, v62
	v_mul_f32_e32 v137, v63, v63
	v_mul_f32_e32 v139, v64, v64
	v_mul_f32_e32 v141, v65, v65
	v_pk_add_f32 v[128:129], v[128:129], v[136:137]
	v_pk_add_f32 v[136:137], v[138:139], v[140:141]
	s_nop 0
	v_pk_add_f32 v[128:129], v[128:129], v[136:137]
	v_add_co_u32_e32 v136, vcc, s63, v126
	v_add_f32_e32 v128, v128, v129
	ds_bpermute_b32 v129, v156, v128
	v_addc_co_u32_e32 v137, vcc, 0, v127, vcc
	v_add_co_u32_e32 v126, vcc, s62, v126
	s_waitcnt lgkmcnt(0)
	v_add_f32_e32 v128, v128, v129
	ds_bpermute_b32 v129, v157, v128
	v_addc_co_u32_e32 v127, vcc, 0, v127, vcc
	s_waitcnt lgkmcnt(0)
	v_add_f32_e32 v128, v128, v129
	ds_bpermute_b32 v129, v158, v128
	s_waitcnt lgkmcnt(0)
	v_add_f32_e32 v128, v128, v129
	ds_bpermute_b32 v129, v159, v128
	s_waitcnt lgkmcnt(0)
	v_add_f32_e32 v128, v128, v129
	ds_bpermute_b32 v129, v160, v128
	s_waitcnt lgkmcnt(0)
	v_add_f32_e32 v128, v128, v129
	ds_bpermute_b32 v129, v161, v128
	s_waitcnt lgkmcnt(0)
	v_add_f32_e32 v128, v128, v129
	v_fmamk_f32 v128, v128, 0x39800000, v131
	v_rsq_f32_e32 v128, v128
	s_nop 0
	v_pk_mul_f32 v[50:51], v[50:51], v[128:129] op_sel_hi:[1,0]
	v_pk_mul_f32 v[52:53], v[52:53], v[128:129] op_sel_hi:[1,0]
	v_pk_mul_f32 v[58:59], v[58:59], v[128:129] op_sel_hi:[1,0]
	v_pk_mul_f32 v[60:61], v[60:61], v[128:129] op_sel_hi:[1,0]
	v_pk_mul_f32 v[54:55], v[54:55], v[128:129] op_sel_hi:[1,0]
	v_pk_mul_f32 v[56:57], v[56:57], v[128:129] op_sel_hi:[1,0]
	v_pk_mul_f32 v[46:47], v[46:47], v[128:129] op_sel_hi:[1,0]
	v_pk_mul_f32 v[48:49], v[48:49], v[128:129] op_sel_hi:[1,0]
	v_pk_mul_f32 v[30:31], v[30:31], v[128:129] op_sel_hi:[1,0]
	v_pk_mul_f32 v[32:33], v[32:33], v[128:129] op_sel_hi:[1,0]
	v_pk_mul_f32 v[38:39], v[38:39], v[128:129] op_sel_hi:[1,0]
	s_waitcnt vmcnt(0)
	v_pk_mul_f32 v[50:51], v[132:133], v[50:51]
	v_pk_mul_f32 v[52:53], v[134:135], v[52:53]
	v_cvt_pk_bf16_f32 v50, v50, v51
	v_cvt_pk_bf16_f32 v51, v52, v53
	global_store_dwordx2 v[136:137], v[50:51], off offset:-4096
	global_load_dwordx4 v[50:53], v[96:97], off offset:1024
	v_pk_mul_f32 v[40:41], v[40:41], v[128:129] op_sel_hi:[1,0]
	v_pk_mul_f32 v[34:35], v[34:35], v[128:129] op_sel_hi:[1,0]
	v_pk_mul_f32 v[36:37], v[36:37], v[128:129] op_sel_hi:[1,0]
	v_pk_mul_f32 v[26:27], v[26:27], v[128:129] op_sel_hi:[1,0]
	v_pk_mul_f32 v[28:29], v[28:29], v[128:129] op_sel_hi:[1,0]
	v_pk_mul_f32 v[22:23], v[22:23], v[128:129] op_sel_hi:[1,0]
	v_pk_mul_f32 v[24:25], v[24:25], v[128:129] op_sel_hi:[1,0]
	v_pk_mul_f32 v[18:19], v[18:19], v[128:129] op_sel_hi:[1,0]
	v_pk_mul_f32 v[20:21], v[20:21], v[128:129] op_sel_hi:[1,0]
	v_pk_mul_f32 v[14:15], v[14:15], v[128:129] op_sel_hi:[1,0]
	v_pk_mul_f32 v[16:17], v[16:17], v[128:129] op_sel_hi:[1,0]
	v_pk_mul_f32 v[10:11], v[10:11], v[128:129] op_sel_hi:[1,0]
	v_pk_mul_f32 v[12:13], v[12:13], v[128:129] op_sel_hi:[1,0]
	v_pk_mul_f32 v[2:3], v[2:3], v[128:129] op_sel_hi:[1,0]
	v_pk_mul_f32 v[4:5], v[4:5], v[128:129] op_sel_hi:[1,0]
	v_pk_mul_f32 v[6:7], v[6:7], v[128:129] op_sel_hi:[1,0]
	v_pk_mul_f32 v[8:9], v[8:9], v[128:129] op_sel_hi:[1,0]
	s_waitcnt vmcnt(0)
	v_pk_mul_f32 v[50:51], v[50:51], v[58:59]
	v_pk_mul_f32 v[52:53], v[52:53], v[60:61]
	v_cvt_pk_bf16_f32 v50, v50, v51
	v_cvt_pk_bf16_f32 v51, v52, v53
	global_store_dwordx2 v[126:127], v[50:51], off offset:512
	global_load_dwordx4 v[50:53], v[96:97], off offset:2048
	s_waitcnt vmcnt(0)
	v_pk_mul_f32 v[50:51], v[50:51], v[54:55]
	v_pk_mul_f32 v[52:53], v[52:53], v[56:57]
	v_cvt_pk_bf16_f32 v50, v50, v51
	v_cvt_pk_bf16_f32 v51, v52, v53
	global_store_dwordx2 v[126:127], v[50:51], off offset:1024
	global_load_dwordx4 v[50:53], v[96:97], off offset:3072
	s_waitcnt vmcnt(0)
	v_pk_mul_f32 v[46:47], v[50:51], v[46:47]
	v_pk_mul_f32 v[48:49], v[52:53], v[48:49]
	v_cvt_pk_bf16_f32 v46, v46, v47
	v_cvt_pk_bf16_f32 v47, v48, v49
	global_store_dwordx2 v[126:127], v[46:47], off offset:1536
	global_load_dwordx4 v[46:49], v[98:99], off
	s_waitcnt vmcnt(0)
	v_pk_mul_f32 v[30:31], v[46:47], v[30:31]
	v_pk_mul_f32 v[32:33], v[48:49], v[32:33]
	v_cvt_pk_bf16_f32 v30, v30, v31
	v_cvt_pk_bf16_f32 v31, v32, v33
	global_store_dwordx2 v[126:127], v[30:31], off offset:2048
	global_load_dwordx4 v[30:33], v[100:101], off
	s_waitcnt vmcnt(0)
	v_pk_mul_f32 v[30:31], v[38:39], v[30:31]
	v_pk_mul_f32 v[32:33], v[40:41], v[32:33]
	v_cvt_pk_bf16_f32 v30, v30, v31
	v_cvt_pk_bf16_f32 v31, v32, v33
	global_store_dwordx2 v[126:127], v[30:31], off offset:2560
	global_load_dwordx4 v[30:33], v[102:103], off
	v_pk_mul_f32 v[38:39], v[42:43], v[128:129] op_sel_hi:[1,0]
	v_pk_mul_f32 v[40:41], v[44:45], v[128:129] op_sel_hi:[1,0]
	s_waitcnt vmcnt(0)
	v_pk_mul_f32 v[30:31], v[38:39], v[30:31]
	v_pk_mul_f32 v[32:33], v[40:41], v[32:33]
	v_cvt_pk_bf16_f32 v30, v30, v31
	v_cvt_pk_bf16_f32 v31, v32, v33
	global_store_dwordx2 v[126:127], v[30:31], off offset:3072
	global_load_dwordx4 v[30:33], v[104:105], off
	s_waitcnt vmcnt(0)
	v_pk_mul_f32 v[30:31], v[34:35], v[30:31]
	v_pk_mul_f32 v[32:33], v[36:37], v[32:33]
	v_cvt_pk_bf16_f32 v30, v30, v31
	v_cvt_pk_bf16_f32 v31, v32, v33
	global_store_dwordx2 v[126:127], v[30:31], off offset:3584
	global_load_dwordx4 v[30:33], v[106:107], off
	s_waitcnt vmcnt(0)
	v_pk_mul_f32 v[26:27], v[26:27], v[30:31]
	v_pk_mul_f32 v[28:29], v[28:29], v[32:33]
	v_cvt_pk_bf16_f32 v26, v26, v27
	v_cvt_pk_bf16_f32 v27, v28, v29
	global_store_dwordx2 v[136:137], v[26:27], off
	global_load_dwordx4 v[26:29], v[108:109], off
	s_waitcnt vmcnt(0)
	v_pk_mul_f32 v[22:23], v[22:23], v[26:27]
	v_pk_mul_f32 v[24:25], v[24:25], v[28:29]
	v_cvt_pk_bf16_f32 v22, v22, v23
	v_cvt_pk_bf16_f32 v23, v24, v25
	global_store_dwordx2 v[136:137], v[22:23], off offset:512
	global_load_dwordx4 v[22:25], v[110:111], off
	s_waitcnt vmcnt(0)
	v_pk_mul_f32 v[18:19], v[18:19], v[22:23]
	v_pk_mul_f32 v[20:21], v[20:21], v[24:25]
	v_cvt_pk_bf16_f32 v18, v18, v19
	v_cvt_pk_bf16_f32 v19, v20, v21
	global_store_dwordx2 v[136:137], v[18:19], off offset:1024
	global_load_dwordx4 v[18:21], v[112:113], off
	s_waitcnt vmcnt(0)
	v_pk_mul_f32 v[14:15], v[14:15], v[18:19]
	v_pk_mul_f32 v[16:17], v[16:17], v[20:21]
	v_cvt_pk_bf16_f32 v14, v14, v15
	v_cvt_pk_bf16_f32 v15, v16, v17
	global_store_dwordx2 v[136:137], v[14:15], off offset:1536
	global_load_dwordx4 v[14:17], v[114:115], off
	s_waitcnt vmcnt(0)
	v_pk_mul_f32 v[10:11], v[10:11], v[14:15]
	v_pk_mul_f32 v[12:13], v[12:13], v[16:17]
	v_cvt_pk_bf16_f32 v10, v10, v11
	v_cvt_pk_bf16_f32 v11, v12, v13
	global_store_dwordx2 v[136:137], v[10:11], off offset:2048
	global_load_dwordx4 v[10:13], v[116:117], off
	s_waitcnt vmcnt(0)
	v_pk_mul_f32 v[2:3], v[2:3], v[10:11]
	v_pk_mul_f32 v[4:5], v[4:5], v[12:13]
	v_cvt_pk_bf16_f32 v2, v2, v3
	v_cvt_pk_bf16_f32 v3, v4, v5
	global_store_dwordx2 v[136:137], v[2:3], off offset:2560
	global_load_dwordx4 v[2:5], v[118:119], off
	s_waitcnt vmcnt(0)
	v_pk_mul_f32 v[2:3], v[6:7], v[2:3]
	v_pk_mul_f32 v[4:5], v[8:9], v[4:5]
	v_cvt_pk_bf16_f32 v2, v2, v3
	v_cvt_pk_bf16_f32 v3, v4, v5
	global_store_dwordx2 v[136:137], v[2:3], off offset:3072
	global_load_dwordx4 v[2:5], v[120:121], off
	v_pk_mul_f32 v[6:7], v[62:63], v[128:129] op_sel_hi:[1,0]
	v_pk_mul_f32 v[8:9], v[64:65], v[128:129] op_sel_hi:[1,0]
	s_waitcnt vmcnt(0)
	v_pk_mul_f32 v[2:3], v[6:7], v[2:3]
	v_pk_mul_f32 v[4:5], v[8:9], v[4:5]
	v_cvt_pk_bf16_f32 v2, v2, v3
	v_cvt_pk_bf16_f32 v3, v4, v5
	global_store_dwordx2 v[136:137], v[2:3], off offset:3584
	s_cmp_lg_u32 s40, 0x800
	s_cbranch_scc1 .Lp9_orig
	s_cmpk_lt_i32 s14, 0x2000
	s_cbranch_scc1 .LBB0_1558
	s_cmpk_ge_i32 s14, 0x2800
	s_cbranch_scc1 .LBB0_1566
	s_bitcmp1_b32 s14, 0
	s_cbranch_scc1 .LBB0_1566
	s_sub_i32 s14, s14, 0x2000
	s_lshr_b32 s14, s14, 1
	s_add_i32 s14, s14, 0x2000
	s_mov_b32 s15, 0
	s_lshl_b32 s92, s14, 14
	v_or_b32_e32 v124, s92, v66
	v_mov_b32_e32 v125, 0
	s_lshl_b32 s92, s14, 13
	v_lshl_or_b32 v122, v162, 3, s92
	v_mov_b32_e32 v123, 0
	s_branch .LBB0_1558
.Lp9_orig:
	s_cmpk_lt_i32 s14, 0x2400
	s_cbranch_scc0 .LBB0_1566

.LBB0_2064:
	s_waitcnt vmcnt(15)
	v_pk_mul_f32 v[66:67], v[60:61], v[60:61]
	v_pk_mul_f32 v[68:69], v[58:59], v[58:59]
	v_lshl_add_u64 v[74:75], s[28:29], 0, v[130:131]
	v_pk_mov_b32 v[70:71], v[68:69], v[66:67] op_sel:[1,0]
	v_mov_b32_e32 v69, v67
	v_pk_add_f32 v[66:67], v[70:71], v[68:69]
	s_waitcnt vmcnt(14)
	v_pk_mul_f32 v[68:69], v[64:65], v[64:65]
	v_pk_add_f32 v[66:67], v[66:67], v[66:67] op_sel_hi:[0,1]
	v_pk_mul_f32 v[70:71], v[62:63], v[62:63]
	s_waitcnt vmcnt(13)
	v_mul_f32_e32 v66, v50, v50
	v_pk_mov_b32 v[72:73], v[70:71], v[68:69] op_sel:[1,0]
	v_mov_b32_e32 v71, v69
	v_pk_add_f32 v[68:69], v[72:73], v[70:71]
	v_pk_fma_f32 v[70:71], v[50:51], v[50:51], v[66:67] op_sel_hi:[1,1,0]
	v_mul_f32_e32 v66, v52, v52
	v_pk_add_f32 v[68:69], v[68:69], v[68:69] op_sel_hi:[0,1]
	v_pk_fma_f32 v[72:73], v[52:53], v[52:53], v[66:67] op_sel_hi:[1,1,0]
	s_waitcnt vmcnt(12)
	v_mul_f32_e32 v70, v46, v46
	v_mul_f32_e32 v72, v47, v47
	v_mul_f32_e32 v68, v48, v48
	v_mul_f32_e32 v66, v49, v49
	v_pk_add_f32 v[70:71], v[70:71], v[72:73]
	v_pk_add_f32 v[66:67], v[68:69], v[66:67]
	s_waitcnt vmcnt(11)
	v_pk_mul_f32 v[68:69], v[8:9], v[8:9]
	v_pk_add_f32 v[66:67], v[70:71], v[66:67]
	v_pk_mul_f32 v[70:71], v[6:7], v[6:7]
	v_pk_add_f32 v[66:67], v[66:67], v[66:67] op_sel_hi:[0,1]
	v_pk_mov_b32 v[72:73], v[70:71], v[68:69] op_sel:[1,0]
	v_mov_b32_e32 v71, v69
	s_waitcnt vmcnt(10)
	v_mul_f32_e32 v66, v18, v18
	v_pk_add_f32 v[68:69], v[72:73], v[70:71]
	v_pk_fma_f32 v[70:71], v[18:19], v[18:19], v[66:67] op_sel_hi:[1,1,0]
	v_mul_f32_e32 v66, v20, v20
	v_pk_add_f32 v[68:69], v[68:69], v[68:69] op_sel_hi:[0,1]
	v_pk_fma_f32 v[72:73], v[20:21], v[20:21], v[66:67] op_sel_hi:[1,1,0]
	s_waitcnt vmcnt(9)
	v_mul_f32_e32 v70, v34, v34
	v_mul_f32_e32 v72, v35, v35
	v_mul_f32_e32 v68, v36, v36
	v_mul_f32_e32 v66, v37, v37
	v_pk_add_f32 v[70:71], v[70:71], v[72:73]
	v_pk_add_f32 v[66:67], v[68:69], v[66:67]
	s_waitcnt vmcnt(8)
	v_pk_mul_f32 v[68:69], v[40:41], v[40:41]
	v_pk_add_f32 v[66:67], v[70:71], v[66:67]
	v_pk_mul_f32 v[70:71], v[38:39], v[38:39]
	v_pk_add_f32 v[66:67], v[66:67], v[66:67] op_sel_hi:[0,1]
	v_pk_mov_b32 v[72:73], v[70:71], v[68:69] op_sel:[1,0]
	v_mov_b32_e32 v71, v69
	s_waitcnt vmcnt(7)
	v_mul_f32_e32 v66, v22, v22
	v_pk_add_f32 v[68:69], v[72:73], v[70:71]
	v_pk_fma_f32 v[70:71], v[22:23], v[22:23], v[66:67] op_sel_hi:[1,1,0]
	v_mul_f32_e32 v66, v24, v24
	v_pk_add_f32 v[68:69], v[68:69], v[68:69] op_sel_hi:[0,1]
	v_pk_fma_f32 v[72:73], v[24:25], v[24:25], v[66:67] op_sel_hi:[1,1,0]
	s_waitcnt vmcnt(6)
	v_mul_f32_e32 v70, v30, v30
	v_mul_f32_e32 v72, v31, v31
	v_mul_f32_e32 v68, v32, v32
	v_mul_f32_e32 v66, v33, v33
	v_pk_add_f32 v[70:71], v[70:71], v[72:73]
	v_pk_add_f32 v[66:67], v[68:69], v[66:67]
	s_waitcnt vmcnt(5)
	v_pk_mul_f32 v[138:139], v[28:29], v[28:29]
	v_pk_add_f32 v[66:67], v[70:71], v[66:67]
	v_pk_mul_f32 v[140:141], v[26:27], v[26:27]
	v_pk_add_f32 v[76:77], v[66:67], v[66:67] op_sel_hi:[0,1]
	global_load_dwordx4 v[66:69], v[74:75], off
	global_load_dwordx4 v[70:73], v[80:81], off
	v_pk_mov_b32 v[142:143], v[140:141], v[138:139] op_sel:[1,0]
	v_mov_b32_e32 v141, v139
	s_waitcnt vmcnt(6)
	v_mul_f32_e32 v76, v42, v42
	v_pk_add_f32 v[138:139], v[142:143], v[140:141]
	v_pk_fma_f32 v[140:141], v[42:43], v[42:43], v[76:77] op_sel_hi:[1,1,0]
	v_mul_f32_e32 v76, v44, v44
	v_pk_add_f32 v[138:139], v[138:139], v[138:139] op_sel_hi:[0,1]
	v_pk_fma_f32 v[142:143], v[44:45], v[44:45], v[76:77] op_sel_hi:[1,1,0]
	s_waitcnt vmcnt(5)
	v_mul_f32_e32 v140, v2, v2
	v_mul_f32_e32 v142, v3, v3
	v_mul_f32_e32 v138, v4, v4
	v_mul_f32_e32 v76, v5, v5
	v_pk_add_f32 v[140:141], v[140:141], v[142:143]
	v_pk_add_f32 v[76:77], v[138:139], v[76:77]
	s_waitcnt vmcnt(4)
	v_pk_mul_f32 v[138:139], v[12:13], v[12:13]
	v_pk_add_f32 v[76:77], v[140:141], v[76:77]
	v_pk_mul_f32 v[140:141], v[10:11], v[10:11]
	v_pk_add_f32 v[76:77], v[76:77], v[76:77] op_sel_hi:[0,1]
	v_pk_mov_b32 v[142:143], v[140:141], v[138:139] op_sel:[1,0]
	v_mov_b32_e32 v141, v139
	s_waitcnt vmcnt(3)
	v_mul_f32_e32 v76, v14, v14
	v_pk_add_f32 v[138:139], v[142:143], v[140:141]
	v_pk_fma_f32 v[140:141], v[14:15], v[14:15], v[76:77] op_sel_hi:[1,1,0]
	v_mul_f32_e32 v76, v16, v16
	v_pk_add_f32 v[138:139], v[138:139], v[138:139] op_sel_hi:[0,1]
	v_pk_fma_f32 v[142:143], v[16:17], v[16:17], v[76:77] op_sel_hi:[1,1,0]
	s_waitcnt vmcnt(2)
	v_mul_f32_e32 v140, v54, v54
	v_mul_f32_e32 v142, v55, v55
	v_mul_f32_e32 v138, v56, v56
	v_mul_f32_e32 v76, v57, v57
	v_pk_add_f32 v[140:141], v[140:141], v[142:143]
	v_pk_add_f32 v[76:77], v[138:139], v[76:77]
	s_add_i32 s42, s42, s40
	v_pk_add_f32 v[76:77], v[140:141], v[76:77]
	v_lshl_add_u64 v[134:135], v[134:135], 0, s[8:9]
	v_add_f32_e32 v76, v76, v77
	ds_bpermute_b32 v77, v1, v76
	s_cmpk_lt_i32 s42, 0x2400
	v_lshl_add_u64 v[130:131], v[130:131], 0, s[10:11]
	s_waitcnt lgkmcnt(0)
	v_add_f32_e32 v76, v76, v77
	ds_bpermute_b32 v77, v144, v76
	s_waitcnt lgkmcnt(0)
	v_add_f32_e32 v76, v76, v77
	ds_bpermute_b32 v77, v145, v76
	s_waitcnt lgkmcnt(0)
	v_add_f32_e32 v76, v76, v77
	ds_bpermute_b32 v77, v146, v76
	s_waitcnt lgkmcnt(0)
	v_add_f32_e32 v76, v76, v77
	ds_bpermute_b32 v77, v147, v76
	s_waitcnt lgkmcnt(0)
	v_add_f32_e32 v76, v76, v77
	ds_bpermute_b32 v77, v148, v76
	s_waitcnt lgkmcnt(0)
	v_add_f32_e32 v76, v76, v77
	v_fmamk_f32 v76, v76, 0x39800000, v149
	v_rsq_f32_e32 v138, v76
	s_nop 0
	v_pk_mul_f32 v[76:77], v[58:59], v[138:139] op_sel_hi:[1,0]
	v_pk_mul_f32 v[140:141], v[60:61], v[138:139] op_sel_hi:[1,0]
	s_waitcnt vmcnt(0)
	v_pk_fma_f32 v[66:67], v[70:71], v[76:77], v[66:67]
	v_pk_fma_f32 v[68:69], v[72:73], v[140:141], v[68:69]
	global_store_dwordx4 v[74:75], v[66:69], off
	global_load_dwordx4 v[58:61], v[74:75], off offset:1024
	global_load_dwordx4 v[70:73], v[80:81], off offset:1024
	v_pk_mul_f32 v[64:65], v[64:65], v[138:139] op_sel_hi:[1,0]
	v_pk_mul_f32 v[62:63], v[62:63], v[138:139] op_sel_hi:[1,0]
	v_pk_mul_f32 v[52:53], v[52:53], v[138:139] op_sel_hi:[1,0]
	v_pk_mul_f32 v[50:51], v[50:51], v[138:139] op_sel_hi:[1,0]
	v_pk_mul_f32 v[46:47], v[46:47], v[138:139] op_sel_hi:[1,0]
	v_pk_mul_f32 v[48:49], v[48:49], v[138:139] op_sel_hi:[1,0]
	v_add_co_u32_e32 v140, vcc, s16, v74
	v_pk_mul_f32 v[8:9], v[8:9], v[138:139] op_sel_hi:[1,0]
	s_nop 0
	v_addc_co_u32_e32 v141, vcc, 0, v75, vcc
	v_add_co_u32_e32 v142, vcc, s18, v74
	v_pk_mul_f32 v[6:7], v[6:7], v[138:139] op_sel_hi:[1,0]
	s_nop 0
	v_addc_co_u32_e32 v143, vcc, 0, v75, vcc
	v_add_co_u32_e32 v166, vcc, s19, v74
	v_pk_mul_f32 v[20:21], v[20:21], v[138:139] op_sel_hi:[1,0]
	s_nop 0
	v_addc_co_u32_e32 v167, vcc, 0, v75, vcc
	v_pk_mul_f32 v[18:19], v[18:19], v[138:139] op_sel_hi:[1,0]
	v_pk_mul_f32 v[24:25], v[24:25], v[138:139] op_sel_hi:[1,0]
	v_pk_mul_f32 v[22:23], v[22:23], v[138:139] op_sel_hi:[1,0]
	v_pk_mul_f32 v[28:29], v[28:29], v[138:139] op_sel_hi:[1,0]
	v_pk_mul_f32 v[26:27], v[26:27], v[138:139] op_sel_hi:[1,0]
	v_pk_mul_f32 v[2:3], v[2:3], v[138:139] op_sel_hi:[1,0]
	v_pk_mul_f32 v[4:5], v[4:5], v[138:139] op_sel_hi:[1,0]
	v_pk_mul_f32 v[12:13], v[12:13], v[138:139] op_sel_hi:[1,0]
	v_pk_mul_f32 v[10:11], v[10:11], v[138:139] op_sel_hi:[1,0]
	s_waitcnt vmcnt(0)
	v_pk_fma_f32 v[58:59], v[70:71], v[62:63], v[58:59]
	v_pk_fma_f32 v[60:61], v[72:73], v[64:65], v[60:61]
	global_store_dwordx4 v[74:75], v[58:61], off offset:1024
	global_load_dwordx4 v[62:65], v[80:81], off offset:2048
	global_load_dwordx4 v[70:73], v[74:75], off offset:2048
	global_load_dwordx4 v[150:153], v[74:75], off offset:3072
	s_waitcnt vmcnt(1)
	v_pk_fma_f32 v[50:51], v[62:63], v[50:51], v[70:71]
	v_pk_fma_f32 v[52:53], v[64:65], v[52:53], v[72:73]
	global_store_dwordx4 v[74:75], v[50:53], off offset:2048
	global_load_dwordx4 v[70:73], v[80:81], off offset:3072
	global_load_dwordx4 v[62:65], v[140:141], off offset:-4096
	s_waitcnt vmcnt(1)
	v_pk_fma_f32 v[48:49], v[72:73], v[48:49], v[152:153]
	v_pk_fma_f32 v[46:47], v[70:71], v[46:47], v[150:151]
	global_store_dwordx4 v[74:75], v[46:49], off offset:3072
	global_load_dwordx4 v[70:73], v[82:83], off
	global_load_dwordx4 v[150:153], v[166:167], off offset:3072
	s_waitcnt vmcnt(1)
	v_pk_fma_f32 v[74:75], v[70:71], v[6:7], v[62:63]
	v_pk_fma_f32 v[76:77], v[72:73], v[8:9], v[64:65]
	global_store_dwordx4 v[140:141], v[74:77], off offset:-4096
	global_load_dwordx4 v[6:9], v[84:85], off
	global_load_dwordx4 v[62:65], v[142:143], off offset:1024
	global_load_dwordx4 v[154:157], v[142:143], off offset:2048
	s_waitcnt vmcnt(1)
	v_pk_fma_f32 v[70:71], v[6:7], v[18:19], v[62:63]
	v_pk_fma_f32 v[72:73], v[8:9], v[20:21], v[64:65]
	global_store_dwordx4 v[142:143], v[70:73], off offset:1024
	global_load_dwordx4 v[6:9], v[86:87], off
	v_pk_mul_f32 v[18:19], v[34:35], v[138:139] op_sel_hi:[1,0]
	v_pk_mul_f32 v[20:21], v[36:37], v[138:139] op_sel_hi:[1,0]
	v_pk_mul_f32 v[34:35], v[40:41], v[138:139] op_sel_hi:[1,0]
	v_pk_mul_f32 v[36:37], v[38:39], v[138:139] op_sel_hi:[1,0]
	s_waitcnt vmcnt(0)
	v_pk_fma_f32 v[64:65], v[8:9], v[20:21], v[156:157]
	v_pk_fma_f32 v[62:63], v[6:7], v[18:19], v[154:155]
	global_store_dwordx4 v[142:143], v[62:65], off offset:2048
	global_load_dwordx4 v[6:9], v[88:89], off
	global_load_dwordx4 v[18:21], v[142:143], off offset:3072
	global_load_dwordx4 v[154:157], v[166:167], off
	s_waitcnt vmcnt(1)
	v_pk_fma_f32 v[38:39], v[6:7], v[36:37], v[18:19]
	v_pk_fma_f32 v[40:41], v[8:9], v[34:35], v[20:21]
	global_store_dwordx4 v[142:143], v[38:41], off offset:3072
	global_load_dwordx4 v[6:9], v[90:91], off
	global_load_dwordx4 v[18:21], v[140:141], off
	global_load_dwordx4 v[158:161], v[140:141], off offset:1024
	s_waitcnt vmcnt(1)
	v_pk_fma_f32 v[34:35], v[22:23], v[6:7], v[18:19]
	v_pk_fma_f32 v[36:37], v[24:25], v[8:9], v[20:21]
	global_store_dwordx4 v[140:141], v[34:37], off
	global_load_dwordx4 v[6:9], v[92:93], off
	v_pk_mul_f32 v[18:19], v[30:31], v[138:139] op_sel_hi:[1,0]
	v_pk_mul_f32 v[20:21], v[32:33], v[138:139] op_sel_hi:[1,0]
	s_waitcnt vmcnt(0)
	v_pk_fma_f32 v[30:31], v[18:19], v[6:7], v[158:159]
	v_pk_fma_f32 v[32:33], v[20:21], v[8:9], v[160:161]
	global_store_dwordx4 v[140:141], v[30:33], off offset:1024
	global_load_dwordx4 v[6:9], v[94:95], off
	global_load_dwordx4 v[18:21], v[140:141], off offset:2048
	global_load_dwordx4 v[22:25], v[140:141], off offset:3072
	s_waitcnt vmcnt(1)
	v_pk_fma_f32 v[26:27], v[26:27], v[6:7], v[18:19]
	v_pk_fma_f32 v[28:29], v[28:29], v[8:9], v[20:21]
	global_store_dwordx4 v[140:141], v[26:29], off offset:2048
	global_load_dwordx4 v[6:9], v[96:97], off
	v_pk_mul_f32 v[18:19], v[44:45], v[138:139] op_sel_hi:[1,0]
	v_pk_mul_f32 v[20:21], v[42:43], v[138:139] op_sel_hi:[1,0]
	s_waitcnt vmcnt(0)
	v_pk_fma_f32 v[24:25], v[18:19], v[8:9], v[24:25]
	v_pk_fma_f32 v[22:23], v[20:21], v[6:7], v[22:23]
	global_store_dwordx4 v[140:141], v[22:25], off offset:3072
	global_load_dwordx4 v[6:9], v[98:99], off
	s_waitcnt vmcnt(0)
	v_pk_fma_f32 v[20:21], v[4:5], v[8:9], v[156:157]
	v_pk_fma_f32 v[18:19], v[2:3], v[6:7], v[154:155]
	global_store_dwordx4 v[166:167], v[18:21], off
	global_load_dwordx4 v[2:5], v[100:101], off
	global_load_dwordx4 v[6:9], v[166:167], off offset:1024
	global_load_dwordx4 v[42:45], v[166:167], off offset:2048
	s_waitcnt vmcnt(1)
	v_pk_fma_f32 v[6:7], v[10:11], v[2:3], v[6:7]
	v_pk_fma_f32 v[8:9], v[12:13], v[4:5], v[8:9]
	global_store_dwordx4 v[166:167], v[6:9], off offset:1024
	global_load_dwordx4 v[2:5], v[102:103], off
	v_pk_mul_f32 v[10:11], v[16:17], v[138:139] op_sel_hi:[1,0]
	v_pk_mul_f32 v[12:13], v[14:15], v[138:139] op_sel_hi:[1,0]
	v_pk_mul_f32 v[14:15], v[54:55], v[138:139] op_sel_hi:[1,0]
	v_pk_mul_f32 v[16:17], v[56:57], v[138:139] op_sel_hi:[1,0]
	s_waitcnt vmcnt(0)
	v_pk_fma_f32 v[2:3], v[12:13], v[2:3], v[42:43]
	v_pk_fma_f32 v[4:5], v[10:11], v[4:5], v[44:45]
	global_store_dwordx4 v[166:167], v[2:5], off offset:2048
	global_load_dwordx4 v[10:13], v[104:105], off
	v_pk_mul_f32 v[42:43], v[68:69], v[68:69]
	v_pk_mul_f32 v[44:45], v[66:67], v[66:67]
	s_waitcnt vmcnt(0)
	v_pk_fma_f32 v[12:13], v[16:17], v[12:13], v[152:153]
	v_pk_fma_f32 v[10:11], v[14:15], v[10:11], v[150:151]
	v_pk_mov_b32 v[54:55], v[44:45], v[42:43] op_sel:[1,0]
	v_mov_b32_e32 v45, v43
	global_store_dwordx4 v[166:167], v[10:13], off offset:3072
	v_pk_add_f32 v[42:43], v[54:55], v[44:45]
	v_pk_mul_f32 v[44:45], v[58:59], v[58:59]
	v_pk_mul_f32 v[54:55], v[60:61], v[60:61]
	global_load_dwordx4 v[14:17], v[106:107], off
	v_pk_mov_b32 v[56:57], v[44:45], v[54:55] op_sel:[1,0]
	v_mov_b32_e32 v45, v55
	v_pk_add_f32 v[44:45], v[56:57], v[44:45]
	v_pk_add_f32 v[42:43], v[42:43], v[42:43] op_sel_hi:[0,1]
	v_pk_add_f32 v[44:45], v[44:45], v[44:45] op_sel_hi:[0,1]
	v_mul_f32_e32 v42, v50, v50
	v_mul_f32_e32 v44, v52, v52
	v_pk_fma_f32 v[54:55], v[50:51], v[50:51], v[42:43] op_sel_hi:[1,1,0]
	v_pk_fma_f32 v[56:57], v[52:53], v[52:53], v[44:45] op_sel_hi:[1,1,0]
	v_mul_f32_e32 v54, v46, v46
	v_mul_f32_e32 v56, v47, v47
	v_mul_f32_e32 v42, v48, v48
	v_mul_f32_e32 v44, v49, v49
	v_pk_add_f32 v[54:55], v[54:55], v[56:57]
	v_pk_add_f32 v[42:43], v[42:43], v[44:45]
	v_pk_mul_f32 v[44:45], v[74:75], v[74:75]
	v_pk_add_f32 v[42:43], v[54:55], v[42:43]
	v_pk_mul_f32 v[54:55], v[76:77], v[76:77]
	v_pk_add_f32 v[42:43], v[42:43], v[42:43] op_sel_hi:[0,1]
	v_pk_mov_b32 v[56:57], v[44:45], v[54:55] op_sel:[1,0]
	v_mov_b32_e32 v45, v55
	v_pk_add_f32 v[44:45], v[56:57], v[44:45]
	v_mul_f32_e32 v42, v70, v70
	v_pk_add_f32 v[44:45], v[44:45], v[44:45] op_sel_hi:[0,1]
	v_mul_f32_e32 v44, v72, v72
	v_pk_fma_f32 v[54:55], v[70:71], v[70:71], v[42:43] op_sel_hi:[1,1,0]
	v_pk_fma_f32 v[56:57], v[72:73], v[72:73], v[44:45] op_sel_hi:[1,1,0]
	v_mul_f32_e32 v54, v62, v62
	v_mul_f32_e32 v56, v63, v63
	v_mul_f32_e32 v44, v64, v64
	v_mul_f32_e32 v42, v65, v65
	v_pk_add_f32 v[54:55], v[54:55], v[56:57]
	v_pk_add_f32 v[42:43], v[44:45], v[42:43]
	v_pk_mul_f32 v[44:45], v[38:39], v[38:39]
	v_pk_add_f32 v[42:43], v[54:55], v[42:43]
	v_pk_mul_f32 v[54:55], v[40:41], v[40:41]
	v_pk_add_f32 v[42:43], v[42:43], v[42:43] op_sel_hi:[0,1]
	v_pk_mov_b32 v[56:57], v[44:45], v[54:55] op_sel:[1,0]
	v_mov_b32_e32 v45, v55
	v_pk_add_f32 v[44:45], v[56:57], v[44:45]
	v_mul_f32_e32 v42, v34, v34
	v_pk_add_f32 v[44:45], v[44:45], v[44:45] op_sel_hi:[0,1]
	v_mul_f32_e32 v44, v36, v36
	v_pk_fma_f32 v[54:55], v[34:35], v[34:35], v[42:43] op_sel_hi:[1,1,0]
	v_pk_fma_f32 v[56:57], v[36:37], v[36:37], v[44:45] op_sel_hi:[1,1,0]
	v_mul_f32_e32 v54, v30, v30
	v_mul_f32_e32 v56, v31, v31
	v_mul_f32_e32 v44, v32, v32
	v_mul_f32_e32 v42, v33, v33
	v_pk_add_f32 v[54:55], v[54:55], v[56:57]
	v_pk_add_f32 v[42:43], v[44:45], v[42:43]
	v_pk_mul_f32 v[44:45], v[26:27], v[26:27]
	v_pk_add_f32 v[42:43], v[54:55], v[42:43]
	v_pk_mul_f32 v[54:55], v[28:29], v[28:29]
	v_pk_add_f32 v[42:43], v[42:43], v[42:43] op_sel:[0,1] op_sel_hi:[1,0]
	v_pk_mov_b32 v[56:57], v[44:45], v[54:55] op_sel:[1,0]
	v_mov_b32_e32 v45, v55
	v_pk_add_f32 v[44:45], v[56:57], v[44:45]
	v_mul_f32_e32 v54, v23, v23
	v_mul_f32_e32 v56, v25, v25
	v_pk_add_f32 v[44:45], v[44:45], v[44:45] op_sel:[0,1] op_sel_hi:[1,0]
	v_pk_fma_f32 v[54:55], v[22:23], v[22:23], v[54:55] op_sel_hi:[1,1,0]
	v_pk_fma_f32 v[56:57], v[24:25], v[24:25], v[56:57] op_sel_hi:[1,1,0]
	v_mul_f32_e32 v43, v18, v18
	v_mul_f32_e32 v45, v19, v19
	v_mul_f32_e32 v55, v20, v20
	v_mul_f32_e32 v57, v21, v21
	v_pk_add_f32 v[42:43], v[42:43], v[44:45]
	v_pk_add_f32 v[44:45], v[54:55], v[56:57]
	v_pk_mul_f32 v[54:55], v[8:9], v[8:9]
	v_pk_add_f32 v[42:43], v[42:43], v[44:45]
	v_pk_mul_f32 v[44:45], v[6:7], v[6:7]
	v_pk_add_f32 v[42:43], v[42:43], v[42:43] op_sel:[0,1] op_sel_hi:[1,0]
	v_pk_mov_b32 v[56:57], v[44:45], v[54:55] op_sel:[1,0]
	v_mov_b32_e32 v45, v55
	v_pk_add_f32 v[44:45], v[56:57], v[44:45]
	v_mul_f32_e32 v54, v3, v3
	v_mul_f32_e32 v56, v5, v5
	v_pk_add_f32 v[44:45], v[44:45], v[44:45] op_sel:[0,1] op_sel_hi:[1,0]
	v_pk_fma_f32 v[54:55], v[2:3], v[2:3], v[54:55] op_sel_hi:[1,1,0]
	v_pk_fma_f32 v[56:57], v[4:5], v[4:5], v[56:57] op_sel_hi:[1,1,0]
	v_mul_f32_e32 v43, v10, v10
	v_mul_f32_e32 v45, v11, v11
	v_mul_f32_e32 v55, v12, v12
	v_mul_f32_e32 v57, v13, v13
	v_pk_add_f32 v[42:43], v[42:43], v[44:45]
	v_pk_add_f32 v[44:45], v[54:55], v[56:57]
	s_nop 0
	v_pk_add_f32 v[42:43], v[42:43], v[44:45]
	v_add_co_u32_e32 v44, vcc, s46, v136
	v_add_f32_e32 v42, v42, v43
	ds_bpermute_b32 v43, v1, v42
	v_addc_co_u32_e32 v45, vcc, 0, v137, vcc
	s_waitcnt lgkmcnt(0)
	v_add_f32_e32 v42, v42, v43
	ds_bpermute_b32 v43, v144, v42
	s_waitcnt lgkmcnt(0)
	v_add_f32_e32 v42, v42, v43
	ds_bpermute_b32 v43, v145, v42
	s_waitcnt lgkmcnt(0)
	v_add_f32_e32 v42, v42, v43
	ds_bpermute_b32 v43, v146, v42
	s_waitcnt lgkmcnt(0)
	v_add_f32_e32 v42, v42, v43
	ds_bpermute_b32 v43, v147, v42
	s_waitcnt lgkmcnt(0)
	v_add_f32_e32 v42, v42, v43
	ds_bpermute_b32 v43, v148, v42
	s_waitcnt lgkmcnt(0)
	v_add_f32_e32 v42, v42, v43
	v_fmamk_f32 v42, v42, 0x39800000, v149
	v_rsq_f32_e32 v42, v42
	s_nop 0
	v_pk_mul_f32 v[54:55], v[66:67], v[42:43] op_sel_hi:[1,0]
	v_pk_mul_f32 v[56:57], v[68:69], v[42:43] op_sel_hi:[1,0]
	s_waitcnt vmcnt(0)
	v_pk_mul_f32 v[14:15], v[14:15], v[54:55]
	v_pk_mul_f32 v[16:17], v[16:17], v[56:57]
	v_cvt_pk_bf16_f32 v14, v14, v15
	v_cvt_pk_bf16_f32 v15, v16, v17
	global_store_dwordx2 v[44:45], v[14:15], off offset:-4096
	global_load_dwordx4 v[14:17], v[106:107], off offset:1024
	v_pk_mul_f32 v[56:57], v[58:59], v[42:43] op_sel_hi:[1,0]
	v_pk_mul_f32 v[58:59], v[60:61], v[42:43] op_sel_hi:[1,0]
	v_add_co_u32_e32 v54, vcc, s45, v136
	v_pk_mul_f32 v[50:51], v[50:51], v[42:43] op_sel_hi:[1,0]
	s_nop 0
	v_addc_co_u32_e32 v55, vcc, 0, v137, vcc
	v_pk_mul_f32 v[52:53], v[52:53], v[42:43] op_sel_hi:[1,0]
	v_pk_mul_f32 v[46:47], v[46:47], v[42:43] op_sel_hi:[1,0]
	v_pk_mul_f32 v[48:49], v[48:49], v[42:43] op_sel_hi:[1,0]
	v_pk_mul_f32 v[38:39], v[38:39], v[42:43] op_sel_hi:[1,0]
	v_pk_mul_f32 v[40:41], v[40:41], v[42:43] op_sel_hi:[1,0]
	v_pk_mul_f32 v[34:35], v[34:35], v[42:43] op_sel_hi:[1,0]
	v_pk_mul_f32 v[36:37], v[36:37], v[42:43] op_sel_hi:[1,0]
	v_pk_mul_f32 v[30:31], v[30:31], v[42:43] op_sel_hi:[1,0]
	v_pk_mul_f32 v[32:33], v[32:33], v[42:43] op_sel_hi:[1,0]
	v_pk_mul_f32 v[26:27], v[26:27], v[42:43] op_sel_hi:[1,0]
	v_pk_mul_f32 v[28:29], v[28:29], v[42:43] op_sel_hi:[1,0]
	v_pk_mul_f32 v[22:23], v[22:23], v[42:43] op_sel_hi:[1,0]
	v_pk_mul_f32 v[24:25], v[24:25], v[42:43] op_sel_hi:[1,0]
	v_pk_mul_f32 v[18:19], v[18:19], v[42:43] op_sel_hi:[1,0]
	v_pk_mul_f32 v[20:21], v[20:21], v[42:43] op_sel_hi:[1,0]
	v_pk_mul_f32 v[6:7], v[6:7], v[42:43] op_sel_hi:[1,0]
	v_pk_mul_f32 v[8:9], v[8:9], v[42:43] op_sel_hi:[1,0]
	v_pk_mul_f32 v[2:3], v[2:3], v[42:43] op_sel_hi:[1,0]
	v_pk_mul_f32 v[4:5], v[4:5], v[42:43] op_sel_hi:[1,0]
	s_waitcnt vmcnt(0)
	v_pk_mul_f32 v[14:15], v[14:15], v[56:57]
	v_pk_mul_f32 v[16:17], v[16:17], v[58:59]
	v_cvt_pk_bf16_f32 v14, v14, v15
	v_cvt_pk_bf16_f32 v15, v16, v17
	global_store_dwordx2 v[54:55], v[14:15], off offset:512
	global_load_dwordx4 v[14:17], v[106:107], off offset:2048
	s_waitcnt vmcnt(0)
	v_pk_mul_f32 v[14:15], v[14:15], v[50:51]
	v_pk_mul_f32 v[16:17], v[16:17], v[52:53]
	v_cvt_pk_bf16_f32 v14, v14, v15
	v_cvt_pk_bf16_f32 v15, v16, v17
	global_store_dwordx2 v[54:55], v[14:15], off offset:1024
	global_load_dwordx4 v[14:17], v[106:107], off offset:3072
	s_waitcnt vmcnt(0)
	v_pk_mul_f32 v[14:15], v[14:15], v[46:47]
	v_pk_mul_f32 v[16:17], v[16:17], v[48:49]
	v_cvt_pk_bf16_f32 v14, v14, v15
	v_cvt_pk_bf16_f32 v15, v16, v17
	global_store_dwordx2 v[54:55], v[14:15], off offset:1536
	global_load_dwordx4 v[14:17], v[108:109], off
	v_pk_mul_f32 v[46:47], v[74:75], v[42:43] op_sel_hi:[1,0]
	v_pk_mul_f32 v[48:49], v[76:77], v[42:43] op_sel_hi:[1,0]
	s_waitcnt vmcnt(0)
	v_pk_mul_f32 v[14:15], v[14:15], v[46:47]
	v_pk_mul_f32 v[16:17], v[16:17], v[48:49]
	v_cvt_pk_bf16_f32 v14, v14, v15
	v_cvt_pk_bf16_f32 v15, v16, v17
	global_store_dwordx2 v[54:55], v[14:15], off offset:2048
	global_load_dwordx4 v[14:17], v[110:111], off
	v_pk_mul_f32 v[46:47], v[70:71], v[42:43] op_sel_hi:[1,0]
	v_pk_mul_f32 v[48:49], v[72:73], v[42:43] op_sel_hi:[1,0]
	s_waitcnt vmcnt(0)
	v_pk_mul_f32 v[14:15], v[46:47], v[14:15]
	v_pk_mul_f32 v[16:17], v[48:49], v[16:17]
	v_cvt_pk_bf16_f32 v14, v14, v15
	v_cvt_pk_bf16_f32 v15, v16, v17
	global_store_dwordx2 v[54:55], v[14:15], off offset:2560
	global_load_dwordx4 v[14:17], v[112:113], off
	v_pk_mul_f32 v[46:47], v[62:63], v[42:43] op_sel_hi:[1,0]
	v_pk_mul_f32 v[48:49], v[64:65], v[42:43] op_sel_hi:[1,0]
	s_waitcnt vmcnt(0)
	v_pk_mul_f32 v[14:15], v[46:47], v[14:15]
	v_pk_mul_f32 v[16:17], v[48:49], v[16:17]
	v_cvt_pk_bf16_f32 v14, v14, v15
	v_cvt_pk_bf16_f32 v15, v16, v17
	global_store_dwordx2 v[54:55], v[14:15], off offset:3072
	global_load_dwordx4 v[14:17], v[114:115], off
	s_waitcnt vmcnt(0)
	v_pk_mul_f32 v[14:15], v[38:39], v[14:15]
	v_pk_mul_f32 v[16:17], v[40:41], v[16:17]
	v_cvt_pk_bf16_f32 v14, v14, v15
	v_cvt_pk_bf16_f32 v15, v16, v17
	global_store_dwordx2 v[54:55], v[14:15], off offset:3584
	global_load_dwordx4 v[14:17], v[116:117], off
	s_waitcnt vmcnt(0)
	v_pk_mul_f32 v[14:15], v[34:35], v[14:15]
	v_pk_mul_f32 v[16:17], v[36:37], v[16:17]
	v_cvt_pk_bf16_f32 v14, v14, v15
	v_cvt_pk_bf16_f32 v15, v16, v17
	global_store_dwordx2 v[44:45], v[14:15], off
	global_load_dwordx4 v[14:17], v[118:119], off
	s_waitcnt vmcnt(0)
	v_pk_mul_f32 v[14:15], v[30:31], v[14:15]
	v_pk_mul_f32 v[16:17], v[32:33], v[16:17]
	v_cvt_pk_bf16_f32 v14, v14, v15
	v_cvt_pk_bf16_f32 v15, v16, v17
	global_store_dwordx2 v[44:45], v[14:15], off offset:512
	global_load_dwordx4 v[14:17], v[120:121], off
	s_waitcnt vmcnt(0)
	v_pk_mul_f32 v[14:15], v[26:27], v[14:15]
	v_pk_mul_f32 v[16:17], v[28:29], v[16:17]
	v_cvt_pk_bf16_f32 v14, v14, v15
	v_cvt_pk_bf16_f32 v15, v16, v17
	global_store_dwordx2 v[44:45], v[14:15], off offset:1024
	global_load_dwordx4 v[14:17], v[122:123], off
	s_waitcnt vmcnt(0)
	v_pk_mul_f32 v[14:15], v[22:23], v[14:15]
	v_pk_mul_f32 v[16:17], v[24:25], v[16:17]
	v_cvt_pk_bf16_f32 v14, v14, v15
	v_cvt_pk_bf16_f32 v15, v16, v17
	global_store_dwordx2 v[44:45], v[14:15], off offset:1536
	global_load_dwordx4 v[14:17], v[124:125], off
	s_waitcnt vmcnt(0)
	v_pk_mul_f32 v[14:15], v[18:19], v[14:15]
	v_pk_mul_f32 v[16:17], v[20:21], v[16:17]
	v_cvt_pk_bf16_f32 v14, v14, v15
	v_cvt_pk_bf16_f32 v15, v16, v17
	global_store_dwordx2 v[44:45], v[14:15], off offset:2048
	global_load_dwordx4 v[14:17], v[126:127], off
	s_waitcnt vmcnt(0)
	v_pk_mul_f32 v[6:7], v[6:7], v[14:15]
	v_pk_mul_f32 v[8:9], v[8:9], v[16:17]
	v_cvt_pk_bf16_f32 v6, v6, v7
	v_cvt_pk_bf16_f32 v7, v8, v9
	global_store_dwordx2 v[44:45], v[6:7], off offset:2560
	global_load_dwordx4 v[6:9], v[128:129], off
	s_waitcnt vmcnt(0)
	v_pk_mul_f32 v[2:3], v[2:3], v[6:7]
	v_pk_mul_f32 v[4:5], v[4:5], v[8:9]
	v_cvt_pk_bf16_f32 v2, v2, v3
	v_cvt_pk_bf16_f32 v3, v4, v5
	global_store_dwordx2 v[44:45], v[2:3], off offset:3072
	global_load_dwordx4 v[2:5], v[132:133], off
	v_pk_mul_f32 v[6:7], v[10:11], v[42:43] op_sel_hi:[1,0]
	v_pk_mul_f32 v[8:9], v[12:13], v[42:43] op_sel_hi:[1,0]
	s_waitcnt vmcnt(0)
	v_pk_mul_f32 v[2:3], v[6:7], v[2:3]
	v_pk_mul_f32 v[4:5], v[8:9], v[4:5]
	v_cvt_pk_bf16_f32 v2, v2, v3
	v_cvt_pk_bf16_f32 v3, v4, v5
	global_store_dwordx2 v[44:45], v[2:3], off offset:3584
	s_cmp_lg_u32 s40, 0x800
	s_cbranch_scc1 .Lp13_orig
	s_cmpk_lt_i32 s42, 0x2000
	s_cbranch_scc1 .LBB0_2065
	s_cmpk_ge_i32 s42, 0x2800
	s_cbranch_scc1 .LBB0_2073
	s_bitcmp1_b32 s42, 0
	s_cbranch_scc1 .LBB0_2073
	s_sub_i32 s42, s42, 0x2000
	s_lshr_b32 s42, s42, 1
	s_add_i32 s42, s42, 0x2000
	s_lshl_b32 s92, s42, 14
	v_lshl_or_b32 v130, v162, 4, s92
	v_mov_b32_e32 v131, 0
	s_lshl_b32 s92, s42, 13
	v_lshl_or_b32 v134, v162, 3, s92
	v_mov_b32_e32 v135, 0
	s_branch .LBB0_2065
.Lp13_orig:
	s_cmpk_lt_i32 s42, 0x2400
	s_cbranch_scc0 .LBB0_2073
